# v29 + attention unit-loop header waits only lgkmcnt before the LDS-reuse barrier (previous unit's output-store acks no longer drained there)
# baseline (speedup 1.0000x reference)
.LBB0_450:
	v_mov_b32_e32 v124, v0
	s_waitcnt lgkmcnt(0)
	s_barrier
	v_readlane_b32 s56, v197, 2
	v_and_b32_e32 v125, 63, v124
	v_lshlrev_b32_e32 v126, 2, v125
	v_readlane_b32 s62, v197, 8
	v_readlane_b32 s63, v197, 9
	v_readlane_b32 s58, v197, 4
	v_readlane_b32 s59, v197, 5
	v_readlane_b32 s60, v197, 6
	v_readlane_b32 s61, v197, 7
	v_readlane_b32 s64, v197, 10
	v_readlane_b32 s65, v197, 11
	v_readlane_b32 s66, v197, 12
	v_readlane_b32 s67, v197, 13
	v_readlane_b32 s68, v197, 14
	v_readlane_b32 s69, v197, 15
	global_load_dword v4, v126, s[62:63]
	global_load_dword v5, v126, s[64:65]
	s_nop 0
	global_load_dword v6, v126, s[66:67]
	s_nop 0
	global_load_dword v7, v126, s[68:69]
	global_load_dword v8, v126, s[58:59]
	global_load_dword v9, v126, s[60:61]
	s_ashr_i32 s4, s17, 5
	s_mul_hi_i32 s12, s17, 0x2aaaaaab
	s_lshl_b32 s5, s17, 7
	s_mul_hi_i32 s13, s4, 0x2aaaaaab
	s_lshr_b32 s18, s12, 31
	s_ashr_i32 s12, s12, 5
	v_ashrrev_i32_e32 v14, 6, v124
	v_cmp_lt_i32_e32 vcc, v115, v114
	s_and_b32 s5, s5, 0xf80
	s_lshr_b32 s19, s13, 31
	s_add_i32 s20, s12, s18
	v_and_b32_e32 v128, 3, v14
	v_cndmask_b32_e32 v2, v105, v115, vcc
	v_and_b32_e32 v15, 15, v124
	s_add_i32 s12, s13, s19
	s_lshl_b32 s13, s20, 12
	v_lshl_or_b32 v16, v128, 5, s5
	v_lshlrev_b32_e32 v122, 2, v2
	v_or3_b32 v108, v16, s13, v15
	v_cmp_lt_i32_e32 vcc, v116, v114
	s_mul_i32 s12, s12, 6
	s_sub_i32 s4, s4, s12
	v_cndmask_b32_e32 v3, v105, v116, vcc
	v_lshlrev_b32_e32 v123, 2, v3
	v_cmp_lt_i32_e32 vcc, v117, v114
	v_readlane_b32 s57, v197, 3
	v_readlane_b32 s70, v197, 16
	v_cndmask_b32_e32 v10, v105, v117, vcc
	v_lshlrev_b32_e32 v10, 2, v10
	v_cmp_lt_i32_e32 vcc, v118, v114
	v_readlane_b32 s71, v197, 17
	s_lshl_b32 s4, s4, 7
	v_cndmask_b32_e32 v11, v105, v118, vcc
	v_lshlrev_b32_e32 v11, 2, v11
	v_cmp_lt_i32_e32 vcc, v119, v114
	s_ashr_i32 s5, s4, 31
	v_readlane_b32 s56, v196, 6
	v_cndmask_b32_e32 v12, v105, v119, vcc
	v_lshlrev_b32_e32 v12, 2, v12
	v_cmp_lt_i32_e32 vcc, v120, v114
	v_ashrrev_i32_e32 v127, 8, v124
	s_lshl_b64 s[12:13], s[4:5], 1
	v_cndmask_b32_e32 v13, v105, v120, vcc
	v_lshlrev_b32_e32 v13, 2, v13
	v_readlane_b32 s60, v196, 10
	v_lshlrev_b32_e32 v2, 6, v127
	v_readlane_b32 s61, v196, 11
	s_add_u32 s18, s60, s12
	v_ashrrev_i32_e32 v3, 31, v2
	s_addc_u32 s19, s61, s13
	v_and_b32_e32 v98, 48, v124
	v_lshl_add_u64 v[2:3], v[2:3], 1, s[18:19]
	s_mov_b32 s18, 0x3f828f5c
	v_lshl_add_u64 v[2:3], v[2:3], 0, v[98:99]
	v_or_b32_e32 v106, 16, v108
	v_bfe_u32 v121, v124, 4, 2
	v_ashrrev_i32_e32 v109, 31, v108
	v_ashrrev_i32_e32 v107, 31, v106
	v_lshlrev_b32_e32 v134, 13, v127
	v_mov_b32_e32 v20, v99
	v_mov_b32_e32 v21, v99
	v_mov_b32_e32 v26, v99
	v_mov_b32_e32 v27, v99
	v_mov_b32_e32 v28, v99
	v_mov_b32_e32 v29, v99
	v_mov_b32_e32 v30, v99
	v_mov_b32_e32 v31, v99
	v_mov_b32_e32 v32, v99
	v_mov_b32_e32 v33, v99
	v_mov_b32_e32 v34, v99
	v_mov_b32_e32 v35, v99
	v_mov_b32_e32 v36, v99
	v_mov_b32_e32 v37, v99
	v_mov_b32_e32 v38, v99
	v_mov_b32_e32 v39, v99
	s_waitcnt vmcnt(4)
	v_mul_f32_e32 v16, v4, v5
	ds_bpermute_b32 v16, v122, v16
	s_waitcnt vmcnt(2)
	v_mul_f32_e32 v17, v6, v7
	s_waitcnt vmcnt(1)
	v_and_b32_e32 v18, 0x7fffffff, v8
	s_waitcnt vmcnt(0)
	v_and_b32_e32 v19, 0x7fffffff, v9
	ds_bpermute_b32 v18, v122, v18
	ds_bpermute_b32 v19, v122, v19
	ds_bpermute_b32 v17, v122, v17
	v_max_f32_e64 v8, |v8|, |v8|
	v_max_f32_e64 v9, |v9|, |v9|
	s_waitcnt lgkmcnt(3)
	v_fmac_f32_e32 v16, v4, v5
	s_waitcnt lgkmcnt(2)
	v_max_f32_e32 v4, v18, v18
	s_waitcnt lgkmcnt(1)
	v_max_f32_e32 v5, v19, v19
	v_max_f32_e32 v4, v8, v4
	v_max_f32_e32 v5, v9, v5
	ds_bpermute_b32 v8, v123, v4
	ds_bpermute_b32 v9, v123, v5
	s_waitcnt lgkmcnt(2)
	v_fmac_f32_e32 v17, v6, v7
	ds_bpermute_b32 v6, v123, v16
	ds_bpermute_b32 v7, v123, v17
	s_waitcnt lgkmcnt(3)
	v_max_f32_e32 v8, v8, v8
	s_waitcnt lgkmcnt(2)
	v_max_f32_e32 v9, v9, v9
	v_max_f32_e32 v4, v4, v8
	v_max_f32_e32 v5, v5, v9
	s_waitcnt lgkmcnt(1)
	v_add_f32_e32 v6, v16, v6
	s_waitcnt lgkmcnt(0)
	v_add_f32_e32 v7, v17, v7
	ds_bpermute_b32 v8, v10, v4
	ds_bpermute_b32 v9, v10, v5
	ds_bpermute_b32 v16, v10, v6
	ds_bpermute_b32 v17, v10, v7
	v_mov_b32_e32 v18, v99
	s_waitcnt lgkmcnt(3)
	v_max_f32_e32 v8, v8, v8
	s_waitcnt lgkmcnt(2)
	v_max_f32_e32 v9, v9, v9
	s_waitcnt lgkmcnt(1)
	v_add_f32_e32 v6, v6, v16
	s_waitcnt lgkmcnt(0)
	v_add_f32_e32 v7, v7, v17
	v_max_f32_e32 v4, v4, v8
	v_max_f32_e32 v5, v5, v9
	ds_bpermute_b32 v10, v11, v6
	ds_bpermute_b32 v16, v11, v7
	ds_bpermute_b32 v8, v11, v4
	ds_bpermute_b32 v9, v11, v5
	v_mov_b32_e32 v19, v99
	s_waitcnt lgkmcnt(3)
	v_add_f32_e32 v6, v6, v10
	s_waitcnt lgkmcnt(2)
	v_add_f32_e32 v7, v7, v16
	s_waitcnt lgkmcnt(1)
	v_max_f32_e32 v8, v8, v8
	s_waitcnt lgkmcnt(0)
	v_max_f32_e32 v9, v9, v9
	ds_bpermute_b32 v10, v12, v6
	ds_bpermute_b32 v11, v12, v7
	v_max_f32_e32 v4, v4, v8
	v_max_f32_e32 v5, v5, v9
	ds_bpermute_b32 v8, v12, v4
	ds_bpermute_b32 v9, v12, v5
	s_waitcnt lgkmcnt(3)
	v_add_f32_e32 v130, v6, v10
	s_waitcnt lgkmcnt(2)
	v_add_f32_e32 v6, v7, v11
	ds_bpermute_b32 v7, v13, v6
	s_waitcnt lgkmcnt(2)
	v_max_f32_e32 v8, v8, v8
	s_waitcnt lgkmcnt(1)
	v_max_f32_e32 v9, v9, v9
	v_max_f32_e32 v4, v4, v8
	v_max_f32_e32 v5, v5, v9
	ds_bpermute_b32 v8, v13, v4
	ds_bpermute_b32 v9, v13, v5
	s_waitcnt lgkmcnt(2)
	v_add_f32_e32 v6, v6, v7
	v_mul_f32_e32 v6, 0x3fb8aa3b, v6
	v_exp_f32_e32 v129, v6
	s_waitcnt lgkmcnt(1)
	v_max_f32_e32 v6, v8, v8
	s_waitcnt lgkmcnt(0)
	v_max_f32_e32 v7, v9, v9
	v_max_f32_e32 v4, v4, v6
	v_max_f32_e32 v5, v5, v7
	v_mul_f32_e32 v4, v4, v5
	v_mul_f32_e32 v4, 0x4138aa3b, v4
	v_fma_f32 v8, v4, s18, 0.5
	v_mad_i64_i32 v[4:5], s[18:19], v108, s14, v[2:3]
	v_mad_i64_i32 v[2:3], s[18:19], v106, s14, v[2:3]
	global_load_dwordx4 v[58:61], v[4:5], off
	global_load_dwordx4 v[50:53], v[4:5], off offset:64
	global_load_dwordx4 v[62:65], v[2:3], off
	global_load_dwordx4 v[54:57], v[2:3], off offset:64
	v_ashrrev_i32_e32 v2, 3, v124
	v_ashrrev_i32_e32 v3, 31, v2
	v_mad_i64_i32 v[4:5], s[18:19], s20, v1, v[2:3]
	v_mad_u64_u32 v[6:7], s[18:19], v4, s14, v[100:101]
	s_mul_hi_i32 s18, s20, 0x300
	s_mulk_i32 s20, 0x300
	s_add_u32 s4, s20, s4
	v_lshrrev_b32_e32 v9, 4, v124
	s_addc_u32 s5, s18, s5
	v_xor_b32_e32 v10, v9, v124
	v_lshl_add_u64 v[2:3], s[4:5], 0, v[2:3]
	v_lshlrev_b32_e32 v4, 4, v10
	v_mad_u64_u32 v[112:113], s[4:5], v2, s15, v[102:103]
	v_and_b32_e32 v98, 0x70, v4
	v_mad_i32_i24 v113, v3, s15, v113
	v_mad_i32_i24 v7, v5, s14, v7
	v_lshl_add_u64 v[2:3], v[112:113], 0, v[98:99]
	s_mov_b64 s[4:5], 0x88000
	v_lshl_add_u64 v[110:111], v[6:7], 0, s[12:13]
	v_lshl_add_u64 v[6:7], v[2:3], 0, s[4:5]
	v_readfirstlane_b32 s4, v14
	s_lshl_b32 s4, s4, 10
	s_add_i32 s4, s4, 0
	v_lshl_add_u64 v[4:5], v[110:111], 0, v[98:99]
	s_mov_b32 m0, s4
	ds_bpermute_b32 v131, v13, v130
	global_load_lds_dwordx4 v[4:5], off
	v_lshl_add_u64 v[4:5], v[4:5], 0, s[2:3]
	s_add_i32 m0, s4, 0x2000
	v_xor_b32_e32 v90, 0x80000000, v8
	global_load_lds_dwordx4 v[4:5], off
	s_add_i32 m0, s4, 0x4000
	v_bfe_u32 v4, v124, 1, 3
	global_load_lds_dwordx4 v[2:3], off
	s_add_i32 m0, s4, 0x6000
	v_lshrrev_b32_e32 v3, 1, v124
	global_load_lds_dwordx4 v[6:7], off
	v_lshlrev_b32_e32 v2, 7, v15
	v_bitop3_b32 v3, v121, v3, 7 bitop3:0x78
	v_lshl_or_b32 v133, v3, 4, v2
	v_bitop3_b32 v3, v121, v4, 4 bitop3:0x36
	v_lshl_or_b32 v132, v3, 4, v2
	v_bitop3_b32 v2, v9, 7, v124 bitop3:0x48
	v_mov_b32_e32 v91, v90
	v_mov_b32_e32 v92, v90
	v_mov_b32_e32 v93, v90
	v_lshlrev_b32_e32 v98, 4, v2
	s_mov_b32 s5, 0
	v_mov_b32_e32 v2, v99
	v_mov_b32_e32 v3, v99
	v_mov_b32_e32 v4, v99
	v_mov_b32_e32 v5, v99
	v_mov_b32_e32 v6, v99
	v_mov_b32_e32 v7, v99
	v_mov_b32_e32 v8, v99
	v_mov_b32_e32 v9, v99
	v_mov_b32_e32 v10, v99
	v_mov_b32_e32 v11, v99
	v_mov_b32_e32 v12, v99
	v_mov_b32_e32 v13, v99
	v_mov_b32_e32 v40, v99
	v_mov_b32_e32 v41, v99
	v_mov_b32_e32 v42, v99
	v_mov_b32_e32 v43, v99
	v_mov_b32_e32 v44, v99
	v_mov_b32_e32 v45, v99
	v_mov_b32_e32 v46, v99
	v_mov_b32_e32 v47, v99
	v_mov_b32_e32 v48, v99
	v_mov_b32_e32 v49, v99
	v_mov_b32_e32 v66, v99
	v_mov_b32_e32 v67, v99
	v_mov_b32_e32 v68, v99
	v_mov_b32_e32 v69, v99
	v_mov_b32_e32 v70, v99
	v_mov_b32_e32 v71, v99
	v_mov_b32_e32 v72, v99
	v_mov_b32_e32 v73, v99
	v_mov_b32_e32 v74, v99
	v_mov_b32_e32 v75, v99
	v_mov_b32_e32 v76, v99
	v_mov_b32_e32 v77, v99
	v_mov_b32_e32 v78, v99
	v_mov_b32_e32 v79, v99
	v_mov_b32_e32 v80, v99
	v_mov_b32_e32 v81, v99
	v_mov_b32_e32 v82, v99
	v_mov_b32_e32 v83, v99
	v_mov_b32_e32 v84, v99
	v_mov_b32_e32 v85, v99
	v_mov_b32_e32 v86, v99
	v_mov_b32_e32 v87, v99
	v_mov_b32_e32 v88, v99
	v_mov_b32_e32 v89, v99
	v_mov_b32_e32 v14, v99
	v_mov_b32_e32 v15, v99
	v_mov_b32_e32 v16, v99
	v_mov_b32_e32 v17, v99
	v_mov_b32_e32 v22, v99
	v_mov_b32_e32 v23, v99
	v_mov_b32_e32 v24, v99
	v_mov_b32_e32 v25, v99
	v_readlane_b32 s57, v196, 7
	v_readlane_b32 s58, v196, 8
	v_readlane_b32 s59, v196, 9
	v_readlane_b32 s62, v196, 12
	v_readlane_b32 s63, v196, 13
	v_readlane_b32 s64, v196, 14
	v_readlane_b32 s65, v196, 15
	v_readlane_b32 s66, v196, 16
	v_readlane_b32 s67, v196, 17
	v_readlane_b32 s68, v196, 18
	v_readlane_b32 s69, v196, 19
	v_readlane_b32 s70, v196, 20
	v_readlane_b32 s71, v196, 21
	s_waitcnt vmcnt(0) lgkmcnt(0)
	s_barrier
	v_lshl_add_u64 v[248:249], v[110:111], 0, v[98:99]
	v_lshl_add_u64 v[252:253], v[112:113], 0, v[98:99]
	s_mov_b64 s[26:27], 0x88000
	v_lshl_add_u64 v[248:249], v[248:249], 0, s[6:7]
	v_lshl_add_u64 v[252:253], v[252:253], 0, s[2:3]
	v_lshl_add_u64 v[250:251], v[248:249], 0, s[2:3]
	v_lshl_add_u64 v[254:255], v[252:253], 0, s[26:27]
	v_mov_b32_e32 v244, s8
	v_mov_b32_e32 v245, s9
	v_mov_b32_e32 v246, s10
	v_mov_b32_e32 v247, s11
	s_mov_b32 s20, 0x8000
	s_mov_b32 s21, 0
	s_mov_b32 s22, 0x10000
	s_mov_b32 s23, 0
	s_add_i32 s25, s4, s20
	s_mov_b32 m0, s25
	s_nop 0
	global_load_lds_dwordx4 v[248:249], off
	s_add_i32 m0, s25, 0x2000
	s_nop 0
	global_load_lds_dwordx4 v[250:251], off
	s_add_i32 m0, s25, 0x4000
	s_nop 0
	global_load_lds_dwordx4 v[252:253], off
	s_add_i32 m0, s25, 0x6000
	s_nop 0
	global_load_lds_dwordx4 v[254:255], off
	v_lshl_add_u64 v[248:249], v[248:249], 0, s[6:7]
	v_lshl_add_u64 v[250:251], v[250:251], 0, s[6:7]
	v_lshl_add_u64 v[252:253], v[252:253], 0, s[2:3]
	v_lshl_add_u64 v[254:255], v[254:255], 0, s[2:3]
	v_add_u32_e32 v94, v134, v133
	v_add_u32_e32 v95, v134, v132
	ds_read_b128 v[204:207], v94
	ds_read_b128 v[208:211], v95
	ds_read_b128 v[212:215], v94 offset:2048
	ds_read_b128 v[216:219], v95 offset:2048
	s_waitcnt lgkmcnt(3)
	v_mfma_f32_16x16x32_bf16 v[136:139], v[204:207], v[58:61], v[90:93]
	v_mfma_f32_16x16x32_bf16 v[140:143], v[204:207], v[62:65], v[90:93]
	ds_read_b128 v[204:207], v94 offset:4096
	s_waitcnt lgkmcnt(3)
	v_mfma_f32_16x16x32_bf16 v[136:139], v[208:211], v[50:53], v[136:139]
	v_mfma_f32_16x16x32_bf16 v[140:143], v[208:211], v[54:57], v[140:143]
	ds_read_b128 v[208:211], v95 offset:4096
	s_waitcnt lgkmcnt(3)
	v_mfma_f32_16x16x32_bf16 v[144:147], v[212:215], v[58:61], v[90:93]
	v_mfma_f32_16x16x32_bf16 v[148:151], v[212:215], v[62:65], v[90:93]
	ds_read_b128 v[212:215], v94 offset:6144
	s_waitcnt lgkmcnt(3)
	v_mfma_f32_16x16x32_bf16 v[144:147], v[216:219], v[50:53], v[144:147]
	v_mfma_f32_16x16x32_bf16 v[148:151], v[216:219], v[54:57], v[148:151]
	ds_read_b128 v[216:219], v95 offset:6144
	s_waitcnt lgkmcnt(3)
	v_mfma_f32_16x16x32_bf16 v[152:155], v[204:207], v[58:61], v[90:93]
	v_mfma_f32_16x16x32_bf16 v[156:159], v[204:207], v[62:65], v[90:93]
	s_waitcnt lgkmcnt(2)
	v_mfma_f32_16x16x32_bf16 v[152:155], v[208:211], v[50:53], v[152:155]
	v_mfma_f32_16x16x32_bf16 v[156:159], v[208:211], v[54:57], v[156:159]
	s_waitcnt lgkmcnt(1)
	v_mfma_f32_16x16x32_bf16 v[160:163], v[212:215], v[58:61], v[90:93]
	v_mfma_f32_16x16x32_bf16 v[164:167], v[212:215], v[62:65], v[90:93]
	s_waitcnt lgkmcnt(0)
	v_mfma_f32_16x16x32_bf16 v[160:163], v[216:219], v[50:53], v[160:163]
	v_mfma_f32_16x16x32_bf16 v[164:167], v[216:219], v[54:57], v[164:167]
	s_nop 7
	v_exp_f32_e32 v136, v136
	v_exp_f32_e32 v137, v137
	v_exp_f32_e32 v138, v138
	v_exp_f32_e32 v139, v139
	v_exp_f32_e32 v144, v144
	v_exp_f32_e32 v145, v145
	v_exp_f32_e32 v146, v146
	v_exp_f32_e32 v147, v147
	v_exp_f32_e32 v140, v140
	v_exp_f32_e32 v141, v141
	v_exp_f32_e32 v142, v142
	v_exp_f32_e32 v143, v143
	v_exp_f32_e32 v148, v148
	v_exp_f32_e32 v149, v149
	v_exp_f32_e32 v150, v150
	v_exp_f32_e32 v151, v151
	v_cvt_pk_bf16_f32 v136, v136, v137
	v_cvt_pk_bf16_f32 v137, v138, v139
	v_cvt_pk_bf16_f32 v138, v144, v145
	v_cvt_pk_bf16_f32 v139, v146, v147
	v_cvt_pk_bf16_f32 v140, v140, v141
	v_cvt_pk_bf16_f32 v141, v142, v143
	v_cvt_pk_bf16_f32 v142, v148, v149
	v_cvt_pk_bf16_f32 v143, v150, v151
	s_waitcnt vmcnt(0) lgkmcnt(0)
	s_barrier
